# v51: v46 + in-proj K-loop laid out so its one taken branch per iteration sits between MFMAs of the last section; non-last iterations fall through from the closing barrier into their first LDS reads
# speedup vs baseline: 1.0093x; 1.0093x over previous
; #define G_STAGE(bufoff, gbase, voff) do { _Pragma("unroll") for (int _i = 0; _i < 2; ++_i) \
;     __builtin_amdgcn_global_load_lds((const unsigned*)((const char*)(gbase) + (voff)[_i]), (LAS unsigned*)(lds + (bufoff) + ldsw + _i * 8192), 16, 0, 0); } while (0)
; #define G_LDA(dst, b, h) do { _Pragma("unroll") for (int m = 0; m < 4; ++m) _Pragma("unroll") for (int k = 0; k < 2; ++k) dst[m][k] = *(const LAS bf16x8*)(lds + G_SA(b, h) + aoff + m * 2048 + k * 1024); } while (0)
; #define G_LDB(dst, b, h) do { _Pragma("unroll") for (int n = 0; n < 2; ++n) _Pragma("unroll") for (int k = 0; k < 2; ++k) dst[n][k] = *(const LAS bf16x8*)(lds + G_SB(b, h) + boff + n * 2048 + k * 1024); } while (0)
; #define G_MMA(ai, bj, At, Bt) do { __builtin_amdgcn_s_setprio(1); _Pragma("unroll") for (int m = 0; m < 4; ++m) _Pragma("unroll") for (int n = 0; n < 2; ++n) _Pragma("unroll") for (int k = 0; k < 2; ++k) \
;     acc[ai][bj][m][n] = __builtin_amdgcn_mfma_f32_16x16x32_bf16(Bt[n][k], At[m][k], acc[ai][bj][m][n], 0, 0, 0); __builtin_amdgcn_s_setprio(0); } while (0)
; #define G_WAIT_V(n) asm volatile("s_waitcnt vmcnt(" #n ")" ::: "memory")
; #define G_WAIT_L(n) asm volatile("s_waitcnt lgkmcnt(" #n ")" ::: "memory")
; #define G_BAR __builtin_amdgcn_s_barrier()
; #define G_SCHED __builtin_amdgcn_sched_barrier(0)
; template <int GP> DI void gemm_phase(const Params& p, int l, int which, char* smem, int wv) {
;     ...
;     for (int t = 0; t < cnk; t += 2) {
;       const bool last = (t == cnk - 2);
;       const char* a1 = cA + (size_t)(t + 1) * kstep;
;       const char* a2 = last ? nA : cA + (size_t)(t + 2) * kstep; const char* b2 = last ? nB : cB + (size_t)(t + 2) * kstep;
;       const char* a3 = a2 + kstep; const char* b3 = b2 + kstep;
;       if (last) {
; #pragma unroll
;         for (int i = 0; i < 2; ++i) { vb0[i] = voffB(i, 0, n32); vb1[i] = voffB(i, 1, n32); }
;       }
;       G_LDB(B0, 0, 0); G_SCHED; G_LDA(At, 0, 0); G_STAGE(G_SA(1, 1), a1 + hstep, voffA);
;       G_WAIT_L(8); G_BAR; G_WAIT_L(0); G_MMA(0, 0, At, B0); G_BAR; G_SCHED;
;       G_LDB(B1, 0, 1); G_STAGE(G_SB(0, 0), b2, vb0);
;       G_BAR; G_WAIT_L(0); G_MMA(0, 1, At, B1); G_BAR;
;       G_LDA(At, 0, 1); G_STAGE(G_SA(0, 0), a2, voffA);
;       G_BAR; G_WAIT_L(0); G_MMA(1, 0, At, B0); G_BAR; G_SCHED;
;       G_STAGE(G_SB(0, 1), b2, vb1);
;       G_WAIT_V(6); G_BAR; G_MMA(1, 1, At, B1); G_BAR;
.LBB0_209:
	s_add_i32 m0, s23, 0xc000
	s_add_u32 s8, s28, s2
	v_add_u32_e32 v228, 0x10000, v212
	s_addc_u32 s9, s29, s3
	s_add_u32 s100, s8, 0x80080
	s_addc_u32 s101, s9, 0
	s_add_u32 s52, s8, 0x100
	s_addc_u32 s53, s9, 0
	s_and_b64 s[8:9], s[6:7], exec
	s_cselect_b32 s9, s10, s53
	s_cselect_b32 s8, s11, s52
	s_add_u32 s52, s74, s2
	s_addc_u32 s53, s75, s3
	s_and_b64 s[6:7], s[6:7], exec
	s_cselect_b32 s7, s37, s53
	s_cselect_b32 s6, s39, s52
	s_branch .Lkf_top
.Lkf_rot:
	v_mfma_f32_16x16x32_bf16 v[118:121], v[238:241], v[184:187], v[118:121]
	v_mfma_f32_16x16x32_bf16 v[122:125], v[200:203], v[192:195], v[122:125]
	v_mfma_f32_16x16x32_bf16 v[126:129], v[238:241], v[192:195], v[126:129]
	s_cmp_gt_u32 s50, 29
	s_barrier
	s_cbranch_scc1 .LBB0_219
	s_cmpk_lg_i32 s2, 0xf00
	s_cbranch_scc0 .LBB0_210
.Lkf_top:
	ds_read_b128 v[148:151], v228
	ds_read_b128 v[152:155], v228 offset:1024
	ds_read_b128 v[156:159], v228 offset:2048
	ds_read_b128 v[160:163], v228 offset:3072
	ds_read_b128 v[164:167], v211
	ds_read_b128 v[168:171], v211 offset:1024
	ds_read_b128 v[172:175], v211 offset:2048
	ds_read_b128 v[176:179], v211 offset:3072
	ds_read_b128 v[180:183], v211 offset:4096
	ds_read_b128 v[184:187], v211 offset:5120
	ds_read_b128 v[188:191], v211 offset:6144
	ds_read_b128 v[192:195], v211 offset:7168
	global_load_lds_dwordx4 v138, s[100:101]
	s_add_i32 m0, s23, 0xe000
	s_nop 0
	global_load_lds_dwordx4 v140, s[100:101]
	s_waitcnt lgkmcnt(8)
	s_barrier
	s_waitcnt lgkmcnt(0)
	v_mfma_f32_16x16x32_bf16 v[62:65], v[148:151], v[164:167], v[62:65]
	v_mfma_f32_16x16x32_bf16 v[58:61], v[156:159], v[164:167], v[58:61]
	s_mov_b32 m0, s25
	v_mfma_f32_16x16x32_bf16 v[54:57], v[148:151], v[172:175], v[54:57]
	v_mfma_f32_16x16x32_bf16 v[50:53], v[156:159], v[172:175], v[50:53]
	v_mfma_f32_16x16x32_bf16 v[46:49], v[148:151], v[180:183], v[46:49]
	v_mfma_f32_16x16x32_bf16 v[42:45], v[156:159], v[180:183], v[42:45]
	v_mfma_f32_16x16x32_bf16 v[38:41], v[148:151], v[188:191], v[38:41]
	v_mfma_f32_16x16x32_bf16 v[34:37], v[156:159], v[188:191], v[34:37]
	v_mfma_f32_16x16x32_bf16 v[62:65], v[152:155], v[168:171], v[62:65]
	v_mfma_f32_16x16x32_bf16 v[58:61], v[160:163], v[168:171], v[58:61]
	v_mfma_f32_16x16x32_bf16 v[54:57], v[152:155], v[176:179], v[54:57]
	v_mfma_f32_16x16x32_bf16 v[50:53], v[160:163], v[176:179], v[50:53]
	v_mfma_f32_16x16x32_bf16 v[46:49], v[152:155], v[184:187], v[46:49]
	v_mfma_f32_16x16x32_bf16 v[42:45], v[160:163], v[184:187], v[42:45]
	v_mfma_f32_16x16x32_bf16 v[38:41], v[152:155], v[192:195], v[38:41]
	v_mfma_f32_16x16x32_bf16 v[34:37], v[160:163], v[192:195], v[34:37]
	s_barrier
	ds_read_b128 v[196:199], v228 offset:16384
	ds_read_b128 v[200:203], v228 offset:17408
	ds_read_b128 v[204:207], v228 offset:18432
	ds_read_b128 v[238:241], v228 offset:19456
	global_load_lds_dwordx4 v0, s[6:7]
	s_mov_b32 m0, s58
	s_nop 0
	global_load_lds_dwordx4 v136, s[6:7]
	s_barrier
	s_waitcnt lgkmcnt(0)
	v_mfma_f32_16x16x32_bf16 v[30:33], v[196:199], v[164:167], v[30:33]
	v_mfma_f32_16x16x32_bf16 v[26:29], v[204:207], v[164:167], v[26:29]
	s_mov_b32 m0, s23
	v_mfma_f32_16x16x32_bf16 v[22:25], v[196:199], v[172:175], v[22:25]
	v_mfma_f32_16x16x32_bf16 v[18:21], v[204:207], v[172:175], v[18:21]
	v_mfma_f32_16x16x32_bf16 v[14:17], v[196:199], v[180:183], v[14:17]
	v_mfma_f32_16x16x32_bf16 v[10:13], v[204:207], v[180:183], v[10:13]
	v_mfma_f32_16x16x32_bf16 v[6:9], v[196:199], v[188:191], v[6:9]
	v_mfma_f32_16x16x32_bf16 v[2:5], v[204:207], v[188:191], v[2:5]
	v_mfma_f32_16x16x32_bf16 v[30:33], v[200:203], v[168:171], v[30:33]
	v_mfma_f32_16x16x32_bf16 v[26:29], v[238:241], v[168:171], v[26:29]
	v_mfma_f32_16x16x32_bf16 v[22:25], v[200:203], v[176:179], v[22:25]
	v_mfma_f32_16x16x32_bf16 v[18:21], v[238:241], v[176:179], v[18:21]
	v_mfma_f32_16x16x32_bf16 v[14:17], v[200:203], v[184:187], v[14:17]
	v_mfma_f32_16x16x32_bf16 v[10:13], v[238:241], v[184:187], v[10:13]
	v_mfma_f32_16x16x32_bf16 v[6:9], v[200:203], v[192:195], v[6:9]
	v_mfma_f32_16x16x32_bf16 v[2:5], v[238:241], v[192:195], v[2:5]
	s_barrier
	ds_read_b128 v[164:167], v211 offset:16384
	ds_read_b128 v[168:171], v211 offset:17408
	ds_read_b128 v[172:175], v211 offset:18432
	ds_read_b128 v[176:179], v211 offset:19456
	ds_read_b128 v[180:183], v211 offset:20480
	ds_read_b128 v[184:187], v211 offset:21504
	ds_read_b128 v[188:191], v211 offset:22528
	ds_read_b128 v[192:195], v211 offset:23552
	global_load_lds_dwordx4 v132, s[8:9]
	s_mov_b32 m0, s59
	s_nop 0
	global_load_lds_dwordx4 v134, s[8:9]
	s_barrier
	s_waitcnt lgkmcnt(0)
	v_mfma_f32_16x16x32_bf16 v[66:69], v[148:151], v[164:167], v[66:69]
	v_mfma_f32_16x16x32_bf16 v[70:73], v[156:159], v[164:167], v[70:73]
	s_mov_b32 m0, s60
	v_mfma_f32_16x16x32_bf16 v[74:77], v[148:151], v[172:175], v[74:77]
	v_mfma_f32_16x16x32_bf16 v[78:81], v[156:159], v[172:175], v[78:81]
	v_mfma_f32_16x16x32_bf16 v[82:85], v[148:151], v[180:183], v[82:85]
	v_mfma_f32_16x16x32_bf16 v[86:89], v[156:159], v[180:183], v[86:89]
	v_mfma_f32_16x16x32_bf16 v[90:93], v[148:151], v[188:191], v[90:93]
	v_mfma_f32_16x16x32_bf16 v[94:97], v[156:159], v[188:191], v[94:97]
	v_mfma_f32_16x16x32_bf16 v[66:69], v[152:155], v[168:171], v[66:69]
	v_mfma_f32_16x16x32_bf16 v[70:73], v[160:163], v[168:171], v[70:73]
	v_mfma_f32_16x16x32_bf16 v[74:77], v[152:155], v[176:179], v[74:77]
	v_mfma_f32_16x16x32_bf16 v[78:81], v[160:163], v[176:179], v[78:81]
	v_mfma_f32_16x16x32_bf16 v[82:85], v[152:155], v[184:187], v[82:85]
	v_mfma_f32_16x16x32_bf16 v[86:89], v[160:163], v[184:187], v[86:89]
	v_mfma_f32_16x16x32_bf16 v[90:93], v[152:155], v[192:195], v[90:93]
	v_mfma_f32_16x16x32_bf16 v[94:97], v[160:163], v[192:195], v[94:97]
	s_barrier
; #define G_STAGE(bufoff, gbase, voff) do { _Pragma("unroll") for (int _i = 0; _i < 2; ++_i) \
;     __builtin_amdgcn_global_load_lds((const unsigned*)((const char*)(gbase) + (voff)[_i]), (LAS unsigned*)(lds + (bufoff) + ldsw + _i * 8192), 16, 0, 0); } while (0)
; #define G_LDA(dst, b, h) do { _Pragma("unroll") for (int m = 0; m < 4; ++m) _Pragma("unroll") for (int k = 0; k < 2; ++k) dst[m][k] = *(const LAS bf16x8*)(lds + G_SA(b, h) + aoff + m * 2048 + k * 1024); } while (0)
; #define G_LDB(dst, b, h) do { _Pragma("unroll") for (int n = 0; n < 2; ++n) _Pragma("unroll") for (int k = 0; k < 2; ++k) dst[n][k] = *(const LAS bf16x8*)(lds + G_SB(b, h) + boff + n * 2048 + k * 1024); } while (0)
; #define G_MMA(ai, bj, At, Bt) do { __builtin_amdgcn_s_setprio(1); _Pragma("unroll") for (int m = 0; m < 4; ++m) _Pragma("unroll") for (int n = 0; n < 2; ++n) _Pragma("unroll") for (int k = 0; k < 2; ++k) \
;     acc[ai][bj][m][n] = __builtin_amdgcn_mfma_f32_16x16x32_bf16(Bt[n][k], At[m][k], acc[ai][bj][m][n], 0, 0, 0); __builtin_amdgcn_s_setprio(0); } while (0)
; #define G_WAIT_V(n) asm volatile("s_waitcnt vmcnt(" #n ")" ::: "memory")
; #define G_WAIT_L(n) asm volatile("s_waitcnt lgkmcnt(" #n ")" ::: "memory")
; #define G_BAR __builtin_amdgcn_s_barrier()
; #define G_SCHED __builtin_amdgcn_sched_barrier(0)
; template <int GP> DI void gemm_phase(const Params& p, int l, int which, char* smem, int wv) {
;     ...
;       G_WAIT_V(6); G_BAR; G_MMA(1, 1, At, B1); G_BAR;
;       G_LDB(B0, 1, 0); G_SCHED; G_LDA(At, 1, 0); G_STAGE(G_SA(0, 1), a2 + hstep, voffA);
;       G_WAIT_L(8); G_BAR; G_WAIT_L(0); G_MMA(0, 0, At, B0); G_BAR; G_SCHED;
;       G_LDB(B1, 1, 1); G_STAGE(G_SB(1, 0), b3, vb0);
;       G_BAR; G_WAIT_L(0); G_MMA(0, 1, At, B1); G_BAR;
;       G_LDA(At, 1, 1); G_STAGE(G_SA(1, 0), a3, voffA);
	global_load_lds_dwordx4 v130, s[6:7]
	s_mov_b32 m0, s61
	s_nop 0
	global_load_lds_dwordx4 v142, s[6:7]
	s_waitcnt vmcnt(6)
	s_barrier
	v_mfma_f32_16x16x32_bf16 v[98:101], v[196:199], v[164:167], v[98:101]
	v_mfma_f32_16x16x32_bf16 v[102:105], v[204:207], v[164:167], v[102:105]
	s_add_u32 s100, s8, 0x80000
	s_addc_u32 s101, s9, 0
	s_mov_b32 m0, s62
	v_mfma_f32_16x16x32_bf16 v[106:109], v[196:199], v[172:175], v[106:109]
	v_mfma_f32_16x16x32_bf16 v[110:113], v[204:207], v[172:175], v[110:113]
	v_mfma_f32_16x16x32_bf16 v[114:117], v[196:199], v[180:183], v[114:117]
	v_mfma_f32_16x16x32_bf16 v[118:121], v[204:207], v[180:183], v[118:121]
	v_mfma_f32_16x16x32_bf16 v[122:125], v[196:199], v[188:191], v[122:125]
	v_mfma_f32_16x16x32_bf16 v[126:129], v[204:207], v[188:191], v[126:129]
	v_mfma_f32_16x16x32_bf16 v[98:101], v[200:203], v[168:171], v[98:101]
	v_mfma_f32_16x16x32_bf16 v[102:105], v[238:241], v[168:171], v[102:105]
	v_mfma_f32_16x16x32_bf16 v[106:109], v[200:203], v[176:179], v[106:109]
	v_mfma_f32_16x16x32_bf16 v[110:113], v[238:241], v[176:179], v[110:113]
	v_mfma_f32_16x16x32_bf16 v[114:117], v[200:203], v[184:187], v[114:117]
	v_mfma_f32_16x16x32_bf16 v[118:121], v[238:241], v[184:187], v[118:121]
	v_mfma_f32_16x16x32_bf16 v[122:125], v[200:203], v[192:195], v[122:125]
	v_mfma_f32_16x16x32_bf16 v[126:129], v[238:241], v[192:195], v[126:129]
	s_barrier
	ds_read_b128 v[148:151], v228 offset:32768
	ds_read_b128 v[152:155], v228 offset:33792
	ds_read_b128 v[156:159], v228 offset:34816
	ds_read_b128 v[160:163], v228 offset:35840
	ds_read_b128 v[164:167], v211 offset:32768
	ds_read_b128 v[168:171], v211 offset:33792
	ds_read_b128 v[172:175], v211 offset:34816
	ds_read_b128 v[176:179], v211 offset:35840
	ds_read_b128 v[180:183], v211 offset:36864
	ds_read_b128 v[184:187], v211 offset:37888
	ds_read_b128 v[188:191], v211 offset:38912
	ds_read_b128 v[192:195], v211 offset:39936
	global_load_lds_dwordx4 v132, s[100:101]
	s_mov_b32 m0, s63
	s_nop 0
	global_load_lds_dwordx4 v134, s[100:101]
	s_waitcnt lgkmcnt(8)
	s_barrier
	s_waitcnt lgkmcnt(0)
	v_mfma_f32_16x16x32_bf16 v[62:65], v[148:151], v[164:167], v[62:65]
	v_mfma_f32_16x16x32_bf16 v[58:61], v[156:159], v[164:167], v[58:61]
	s_mov_b32 m0, s21
	s_add_u32 s100, s6, s16
	s_addc_u32 s101, s7, s17
	v_mfma_f32_16x16x32_bf16 v[54:57], v[148:151], v[172:175], v[54:57]
	v_mfma_f32_16x16x32_bf16 v[50:53], v[156:159], v[172:175], v[50:53]
	v_mfma_f32_16x16x32_bf16 v[46:49], v[148:151], v[180:183], v[46:49]
	v_mfma_f32_16x16x32_bf16 v[42:45], v[156:159], v[180:183], v[42:45]
	v_mfma_f32_16x16x32_bf16 v[38:41], v[148:151], v[188:191], v[38:41]
	v_mfma_f32_16x16x32_bf16 v[34:37], v[156:159], v[188:191], v[34:37]
	v_mfma_f32_16x16x32_bf16 v[62:65], v[152:155], v[168:171], v[62:65]
	v_mfma_f32_16x16x32_bf16 v[58:61], v[160:163], v[168:171], v[58:61]
	v_mfma_f32_16x16x32_bf16 v[54:57], v[152:155], v[176:179], v[54:57]
	v_mfma_f32_16x16x32_bf16 v[50:53], v[160:163], v[176:179], v[50:53]
	v_mfma_f32_16x16x32_bf16 v[46:49], v[152:155], v[184:187], v[46:49]
	v_mfma_f32_16x16x32_bf16 v[42:45], v[160:163], v[184:187], v[42:45]
	v_mfma_f32_16x16x32_bf16 v[38:41], v[152:155], v[192:195], v[38:41]
	v_mfma_f32_16x16x32_bf16 v[34:37], v[160:163], v[192:195], v[34:37]
	s_barrier
	ds_read_b128 v[196:199], v228 offset:49152
	ds_read_b128 v[200:203], v228 offset:50176
	ds_read_b128 v[204:207], v228 offset:51200
	ds_read_b128 v[238:241], v228 offset:52224
	global_load_lds_dwordx4 v0, s[100:101]
	s_mov_b32 m0, s64
	s_nop 0
	global_load_lds_dwordx4 v136, s[100:101]
	s_barrier
; #define G_STAGE(bufoff, gbase, voff) do { _Pragma("unroll") for (int _i = 0; _i < 2; ++_i) \
;     __builtin_amdgcn_global_load_lds((const unsigned*)((const char*)(gbase) + (voff)[_i]), (LAS unsigned*)(lds + (bufoff) + ldsw + _i * 8192), 16, 0, 0); } while (0)
; #define G_LDA(dst, b, h) do { _Pragma("unroll") for (int m = 0; m < 4; ++m) _Pragma("unroll") for (int k = 0; k < 2; ++k) dst[m][k] = *(const LAS bf16x8*)(lds + G_SA(b, h) + aoff + m * 2048 + k * 1024); } while (0)
; #define G_MMA(ai, bj, At, Bt) do { __builtin_amdgcn_s_setprio(1); _Pragma("unroll") for (int m = 0; m < 4; ++m) _Pragma("unroll") for (int n = 0; n < 2; ++n) _Pragma("unroll") for (int k = 0; k < 2; ++k) \
;     acc[ai][bj][m][n] = __builtin_amdgcn_mfma_f32_16x16x32_bf16(Bt[n][k], At[m][k], acc[ai][bj][m][n], 0, 0, 0); __builtin_amdgcn_s_setprio(0); } while (0)
; #define G_WAIT_V(n) asm volatile("s_waitcnt vmcnt(" #n ")" ::: "memory")
; #define G_WAIT_L(n) asm volatile("s_waitcnt lgkmcnt(" #n ")" ::: "memory")
; #define G_BAR __builtin_amdgcn_s_barrier()
; #define G_SCHED __builtin_amdgcn_sched_barrier(0)
; template <int GP> DI void gemm_phase(const Params& p, int l, int which, char* smem, int wv) {
;     ...
;       G_LDA(At, 1, 1); G_STAGE(G_SA(1, 0), a3, voffA);
;       G_BAR; G_WAIT_L(0); G_MMA(1, 0, At, B0); G_BAR; G_SCHED;
;       G_STAGE(G_SB(1, 1), b3, vb1);
;       G_WAIT_V(6); G_BAR; G_MMA(1, 1, At, B1); G_BAR;
	s_waitcnt lgkmcnt(0)
	v_mfma_f32_16x16x32_bf16 v[30:33], v[196:199], v[164:167], v[30:33]
	v_mfma_f32_16x16x32_bf16 v[26:29], v[204:207], v[164:167], v[26:29]
	s_mov_b32 m0, s65
	s_add_u32 s100, s8, s16
	s_addc_u32 s101, s9, s17
	v_mfma_f32_16x16x32_bf16 v[22:25], v[196:199], v[172:175], v[22:25]
	v_mfma_f32_16x16x32_bf16 v[18:21], v[204:207], v[172:175], v[18:21]
	v_mfma_f32_16x16x32_bf16 v[14:17], v[196:199], v[180:183], v[14:17]
	v_mfma_f32_16x16x32_bf16 v[10:13], v[204:207], v[180:183], v[10:13]
	v_mfma_f32_16x16x32_bf16 v[6:9], v[196:199], v[188:191], v[6:9]
	v_mfma_f32_16x16x32_bf16 v[2:5], v[204:207], v[188:191], v[2:5]
	v_mfma_f32_16x16x32_bf16 v[30:33], v[200:203], v[168:171], v[30:33]
	v_mfma_f32_16x16x32_bf16 v[26:29], v[238:241], v[168:171], v[26:29]
	v_mfma_f32_16x16x32_bf16 v[22:25], v[200:203], v[176:179], v[22:25]
	v_mfma_f32_16x16x32_bf16 v[18:21], v[238:241], v[176:179], v[18:21]
	v_mfma_f32_16x16x32_bf16 v[14:17], v[200:203], v[184:187], v[14:17]
	v_mfma_f32_16x16x32_bf16 v[10:13], v[238:241], v[184:187], v[10:13]
	v_mfma_f32_16x16x32_bf16 v[6:9], v[200:203], v[192:195], v[6:9]
	v_mfma_f32_16x16x32_bf16 v[2:5], v[238:241], v[192:195], v[2:5]
	s_barrier
	ds_read_b128 v[164:167], v211 offset:49152
	ds_read_b128 v[168:171], v211 offset:50176
	ds_read_b128 v[172:175], v211 offset:51200
	ds_read_b128 v[176:179], v211 offset:52224
	ds_read_b128 v[180:183], v211 offset:53248
	ds_read_b128 v[184:187], v211 offset:54272
	ds_read_b128 v[188:191], v211 offset:55296
	ds_read_b128 v[192:195], v211 offset:56320
	global_load_lds_dwordx4 v132, s[100:101]
	s_mov_b32 m0, s66
	s_nop 0
	global_load_lds_dwordx4 v134, s[100:101]
	s_barrier
	s_waitcnt lgkmcnt(0)
	v_mfma_f32_16x16x32_bf16 v[66:69], v[148:151], v[164:167], v[66:69]
	v_mfma_f32_16x16x32_bf16 v[70:73], v[156:159], v[164:167], v[70:73]
	s_mov_b32 m0, s67
	s_add_u32 s100, s6, s16
	s_addc_u32 s101, s7, s17
	v_mfma_f32_16x16x32_bf16 v[74:77], v[148:151], v[172:175], v[74:77]
	v_mfma_f32_16x16x32_bf16 v[78:81], v[156:159], v[172:175], v[78:81]
	v_mfma_f32_16x16x32_bf16 v[82:85], v[148:151], v[180:183], v[82:85]
	v_mfma_f32_16x16x32_bf16 v[86:89], v[156:159], v[180:183], v[86:89]
	v_mfma_f32_16x16x32_bf16 v[90:93], v[148:151], v[188:191], v[90:93]
	v_mfma_f32_16x16x32_bf16 v[94:97], v[156:159], v[188:191], v[94:97]
	v_mfma_f32_16x16x32_bf16 v[66:69], v[152:155], v[168:171], v[66:69]
	v_mfma_f32_16x16x32_bf16 v[70:73], v[160:163], v[168:171], v[70:73]
	v_mfma_f32_16x16x32_bf16 v[74:77], v[152:155], v[176:179], v[74:77]
	v_mfma_f32_16x16x32_bf16 v[78:81], v[160:163], v[176:179], v[78:81]
	v_mfma_f32_16x16x32_bf16 v[82:85], v[152:155], v[184:187], v[82:85]
	v_mfma_f32_16x16x32_bf16 v[86:89], v[160:163], v[184:187], v[86:89]
	v_mfma_f32_16x16x32_bf16 v[90:93], v[152:155], v[192:195], v[90:93]
	v_mfma_f32_16x16x32_bf16 v[94:97], v[160:163], v[192:195], v[94:97]
	s_barrier
	global_load_lds_dwordx4 v130, s[100:101]
	s_mov_b32 m0, s68
	s_nop 0
	global_load_lds_dwordx4 v142, s[100:101]
	s_waitcnt vmcnt(6)
	s_barrier
	v_mfma_f32_16x16x32_bf16 v[98:101], v[196:199], v[164:167], v[98:101]
	v_mfma_f32_16x16x32_bf16 v[102:105], v[204:207], v[164:167], v[102:105]
	s_add_i32 m0, s23, 0xc000
	v_mfma_f32_16x16x32_bf16 v[106:109], v[196:199], v[172:175], v[106:109]
	v_mfma_f32_16x16x32_bf16 v[110:113], v[204:207], v[172:175], v[110:113]
	v_mfma_f32_16x16x32_bf16 v[114:117], v[196:199], v[180:183], v[114:117]
	v_mfma_f32_16x16x32_bf16 v[118:121], v[204:207], v[180:183], v[118:121]
	v_mfma_f32_16x16x32_bf16 v[122:125], v[196:199], v[188:191], v[122:125]
	v_mfma_f32_16x16x32_bf16 v[126:129], v[204:207], v[188:191], v[126:129]
	v_mfma_f32_16x16x32_bf16 v[98:101], v[200:203], v[168:171], v[98:101]
	s_add_i32 s50, s50, 2
	s_add_u32 s2, s2, 0x100
	s_addc_u32 s3, s3, 0
	v_mfma_f32_16x16x32_bf16 v[102:105], v[238:241], v[168:171], v[102:105]
	s_add_u32 s8, s28, s2
	s_addc_u32 s9, s29, s3
	v_mfma_f32_16x16x32_bf16 v[106:109], v[200:203], v[176:179], v[106:109]
	s_add_u32 s100, s8, 0x80080
	s_addc_u32 s101, s9, 0
	v_mfma_f32_16x16x32_bf16 v[110:113], v[238:241], v[176:179], v[110:113]
	s_add_u32 s8, s8, 0x100
	s_addc_u32 s9, s9, 0
	v_mfma_f32_16x16x32_bf16 v[114:117], v[200:203], v[184:187], v[114:117]
	s_add_u32 s6, s74, s2
	s_addc_u32 s7, s75, s3
	s_branch .Lkf_rot
